# v41 + staggered rounds: workgroups of virtual XCDs 4-7 run their share of prep_late before the phase-1 tile loop instead of after
# speedup vs baseline: 1.0068x; 1.0068x over previous
_Z10fwd_kernelILin1EEv6Params:
	s_mov_b32 s101, 0
	s_mov_b32 s100, 0
	s_load_dword s3, s[0:1], 0x9c
	s_add_u32 s6, s0, 0x8a0
	s_addc_u32 s7, s1, 0
	s_waitcnt lgkmcnt(0)
	s_cmp_lt_i32 s3, 0
	s_cbranch_scc1 .LBB0_2
	v_and_b32_e32 v218, 0x3ff, v0
	s_load_dwordx2 s[38:39], s[0:1], 0x90
	s_load_dword s33, s[0:1], 0x8a0
	s_cbranch_execz .LBB0_3
	s_branch .LBB0_14

.LBB0_83:
	v_writelane_b32 v250, s20, 2
	v_writelane_b32 v250, s17, 3
	v_writelane_b32 v250, s42, 4
	s_nop 1
	v_writelane_b32 v250, s43, 5
	v_writelane_b32 v250, s40, 6
	s_nop 1
	v_writelane_b32 v250, s41, 7
	s_or_b64 exec, exec, s[6:7]
	s_bitcmp1_b32 s86, 7
	s_cbranch_scc0 .Lpl_skip_early
	s_mov_b32 s100, 1
	s_branch .Lpl_entry
.Lpl_ret_early:
	s_mov_b32 s100, 0
	s_waitcnt vmcnt(0)
.Lpl_skip_early:
	s_load_dwordx4 s[12:15], s[0:1], 0x88
	s_load_dwordx2 s[18:19], s[0:1], 0x68
	v_lshrrev_b32_e32 v0, 2, v218
	v_lshrrev_b32_e32 v1, 1, v218
	v_and_b32_e32 v0, 0xcc, v0
	s_waitcnt lgkmcnt(0)
	s_add_u32 s17, s14, 0x4920000
	s_addc_u32 s95, s15, 0
	s_lshr_b32 s3, s86, 2
	s_and_b32 s3, s3, 56
	s_and_b32 s4, s86, 7
	s_add_i32 s96, s86, 0xfffffb00
	s_and_b32 s93, s86, 63
	s_or_b32 s91, s3, s4
	s_bfe_u32 s94, s86, 0x20003
	s_add_u32 s20, s14, 0xe9a8000
	s_addc_u32 s21, s15, 0
	s_add_u32 s22, s14, 0xe9d8c00
	s_addc_u32 s23, s15, 0
	s_add_u32 s24, s14, 0x77e8000
	s_addc_u32 s25, s15, 0
	s_add_u32 s26, s14, 0x8828000
	s_addc_u32 s27, s15, 0
	s_add_u32 s28, s14, 0x9868000
	s_addc_u32 s29, s15, 0
	s_add_u32 s30, s14, 0x67a8000
	s_addc_u32 s31, s15, 0
	s_add_u32 s34, s14, 0x57e0000
	v_and_b32_e32 v1, 0x60, v1
	s_movk_i32 s97, 0x104
	s_addc_u32 s35, s15, 0
	v_mad_u32_u24 v0, v0, s97, v1
	s_add_u32 s36, s14, 0xe9b8400
	v_writelane_b32 v250, s4, 8
	v_and_or_b32 v0, v218, 15, v0
	s_addc_u32 s37, s15, 0
	s_add_i32 s3, 0, 0x20800
	s_mov_b32 s98, 0
	v_lshl_add_u32 v219, v0, 2, 0
	s_add_i32 s90, 0, 0x10000
	v_mov_b32_e32 v1, 0
	s_movk_i32 s99, 0x80
	s_add_i32 s87, 0, 0x14000
	s_movk_i32 s84, 0x4000
	s_add_i32 s88, 0, 0x18000
	s_mov_b64 s[42:43], 0x80
	s_add_i32 s89, 0, 0x1c000
	s_mov_b64 s[44:45], 0x40080
	s_mov_b64 s[46:47], 0x4920100
	s_mov_b64 s[48:49], 0x100
	s_mov_b64 s[50:51], 0x4960100
	s_mov_b64 s[52:53], 0x40100
	s_mov_b64 s[54:55], 0x4920180
	s_mov_b64 s[56:57], 0x180
	v_writelane_b32 v250, s3, 9
	s_movk_i32 s85, 0x4080
	s_movk_i32 s92, 0x3fff
	s_movk_i32 s3, 0x1ffd
	s_movk_i32 s82, 0x440
	s_movk_i32 s40, 0x140
	v_mov_b32_e32 v215, 0x358637bd
	s_mov_b32 s41, 0x800000
	v_mov_b32_e32 v216, 1
	v_mov_b32_e32 v217, 0x4a92000
	v_mov_b32_e32 v220, 0x4880000
	v_mov_b32_e32 v221, 0x6500000
	v_mov_b32_e32 v222, 0x6000000
	v_mov_b32_e32 v223, 0x4a82000
	v_mov_b32_e32 v224, 0x4080000
	v_mov_b32_e32 v225, 0xfffffe00
	s_mov_b64 s[58:59], 0x4960180
	s_mov_b64 s[60:61], 0x780
	s_barrier
	s_branch .LBB0_86

.LBB0_294:
	s_and_b64 vcc, exec, s[6:7]
	s_cbranch_vccz .LBB0_337
	s_cmp_lt_i32 s86, 20
	s_cbranch_scc1 .LBB0_337
	s_bitcmp1_b32 s86, 7
	s_cbranch_scc1 .LBB0_337
.Lpl_entry:
	s_lshl_b32 s3, s86, 9
	s_add_i32 s4, s3, 0xffffd800
	v_mov_b32_e32 v5, v218
	s_add_i32 s12, s16, 0xffffd800
	v_add_u32_e32 v4, s4, v5
	s_mov_b32 s4, 0x50000
	v_cmp_gt_i32_e32 vcc, s4, v4
	s_and_saveexec_b64 s[6:7], vcc
	s_cbranch_execz .LBB0_304
	s_load_dwordx4 s[20:23], s[0:1], 0x38
	s_waitcnt lgkmcnt(0)
	s_load_dwordx2 s[8:9], s[0:1], 0x50
	v_mov_b32_e32 v0, 2
	v_lshlrev_b32_sdwa v0, v0, v5 dst_sel:DWORD dst_unused:UNUSED_PAD src0_sel:DWORD src1_sel:BYTE_0
	s_movk_i32 s4, 0x300
	global_load_dword v12, v0, s[20:21]
	v_mul_u32_u24_sdwa v0, v5, s4 dst_sel:DWORD dst_unused:UNUSED_PAD src0_sel:BYTE_0 src1_sel:DWORD
	s_add_u32 s10, s38, 0x5320000
	v_lshlrev_b32_e32 v0, 2, v0
	v_mov_b32_e32 v1, 0
	s_addc_u32 s11, s39, 0
	v_lshl_add_u64 v[2:3], s[22:23], 0, v[0:1]
	s_mov_b64 s[14:15], 0
	s_mov_b32 s4, 0x66666667
	s_movk_i32 s5, 0xa0
	s_movk_i32 s13, 0x7f
	s_movk_i32 s17, 0x60
	s_mov_b32 s24, 0x4ffff
	v_mov_b32_e32 v6, v4
	s_branch .LBB0_299

.LBB0_336:
	s_or_b64 exec, exec, s[6:7]
	s_cmp_lg_u32 s100, 0
	s_cbranch_scc1 .Lpl_ret_early
